# ff1 epilogue output stores made write-through (sc1) so the release write-back in the following grid barrier has little dirty data left
# speedup vs baseline: 1.0726x; 1.0726x over previous
.LBB0_2128:
	s_lshl_b32 s0, s8, 8
	s_add_i32 s13, s0, s90
	s_lshl_b32 s0, s9, 8
	v_mov_b32_e32 v156, v160
	v_mov_b32_e32 v157, v161
	s_or_b32 s0, s0, s91
	s_mov_b64 s[34:35], -1
	v_lshl_add_u32 v168, v157, 3, s0
	s_lshl_b32 s0, s8, 10
	s_and_b32 s0, s0, 0xfffff000
	s_addk_i32 s0, 0xd000
	s_cmp_gt_i32 s8, 15
	s_cselect_b32 s96, s0, 0
	v_add_u32_e32 v158, s13, v156
	s_lshl_b64 s[0:1], s[96:97], 2
	v_lshlrev_b32_e32 v156, 2, v157
	v_ashrrev_i32_e32 v159, 31, v158
	s_add_u32 s0, s88, s0
	v_ashrrev_i32_e32 v157, 31, v156
	v_lshlrev_b64 v[164:165], 6, v[158:159]
	s_addc_u32 s1, s89, s1
	v_ashrrev_i32_e32 v169, 31, v168
	v_lshl_add_u64 v[164:165], s[22:23], 0, v[164:165]
	v_lshlrev_b64 v[156:157], 2, v[156:157]
	v_lshl_add_u64 v[32:33], v[168:169], 2, s[0:1]
	v_lshl_add_u64 v[164:165], v[164:165], 0, v[156:157]
	flat_load_dwordx4 v[44:47], v[32:33]
	flat_load_dwordx4 v[40:43], v[32:33] offset:16
	flat_load_dwordx4 v[36:39], v[32:33] offset:512
	s_nop 0
	flat_load_dwordx4 v[32:35], v[32:33] offset:528
	s_nop 0
	flat_load_dwordx4 v[164:167], v[164:165]
	v_add_u32_e32 v172, 16, v158
	v_ashrrev_i32_e32 v173, 31, v172
	v_lshlrev_b64 v[172:173], 6, v[172:173]
	v_lshl_add_u64 v[172:173], s[22:23], 0, v[172:173]
	v_lshl_add_u64 v[172:173], v[172:173], 0, v[156:157]
	global_load_dwordx4 v[172:175], v[172:173], off
	v_add_u32_e32 v176, 32, v158
	v_ashrrev_i32_e32 v177, 31, v176
	v_lshlrev_b64 v[176:177], 6, v[176:177]
	v_lshl_add_u64 v[176:177], s[22:23], 0, v[176:177]
	v_lshl_add_u64 v[176:177], v[176:177], 0, v[156:157]
	global_load_dwordx4 v[176:179], v[176:177], off
	v_add_u32_e32 v184, 48, v158
	v_ashrrev_i32_e32 v185, 31, v184
	v_lshlrev_b64 v[184:185], 6, v[184:185]
	v_lshl_add_u64 v[184:185], s[22:23], 0, v[184:185]
	v_lshl_add_u64 v[184:185], v[184:185], 0, v[156:157]
	global_load_dwordx4 v[184:187], v[184:185], off
	v_add_u32_e32 v196, 0x80, v158
	v_ashrrev_i32_e32 v197, 31, v196
	v_lshlrev_b64 v[196:197], 6, v[196:197]
	v_lshl_add_u64 v[196:197], s[22:23], 0, v[196:197]
	v_lshl_add_u64 v[196:197], v[196:197], 0, v[156:157]
	global_load_dwordx4 v[196:199], v[196:197], off
	v_add_u32_e32 v200, 0x90, v158
	v_ashrrev_i32_e32 v201, 31, v200
	v_lshlrev_b64 v[200:201], 6, v[200:201]
	v_lshl_add_u64 v[200:201], s[22:23], 0, v[200:201]
	v_lshl_add_u64 v[200:201], v[200:201], 0, v[156:157]
	global_load_dwordx4 v[200:203], v[200:201], off
	v_add_u32_e32 v204, 0xa0, v158
	v_ashrrev_i32_e32 v205, 31, v204
	v_lshlrev_b64 v[204:205], 6, v[204:205]
	v_lshl_add_u64 v[204:205], s[22:23], 0, v[204:205]
	v_lshl_add_u64 v[204:205], v[204:205], 0, v[156:157]
	global_load_dwordx4 v[204:207], v[204:205], off
	v_add_u32_e32 v216, 0xb0, v158
	v_ashrrev_i32_e32 v217, 31, v216
	v_lshlrev_b64 v[216:217], 6, v[216:217]
	v_lshl_add_u64 v[216:217], s[22:23], 0, v[216:217]
	v_lshl_add_u64 v[216:217], v[216:217], 0, v[156:157]
	global_load_dwordx4 v[216:219], v[216:217], off
	s_waitcnt vmcnt(0) lgkmcnt(0)
	v_add_f32_e32 v164, v164, v165
	v_add_f32_e32 v165, v166, v167
	v_add_f32_e32 v164, v164, v165
	v_mov_b32_e32 v165, v164
	s_nop 1
	v_permlane16_swap_b32_e32 v164, v165
	v_add_f32_e32 v164, v164, v165
	v_mov_b32_e32 v165, v164
	s_nop 1
	v_permlane32_swap_b32_e32 v164, v165
	v_add_f32_e32 v164, v164, v165
	v_fmamk_f32 v164, v164, 0x3a800000, v229
	v_cmp_gt_f32_e32 vcc, s55, v164
	v_mul_f32_e32 v165, 0x4b800000, v164
	v_lshlrev_b64 v[166:167], 13, v[158:159]
	v_cndmask_b32_e32 v164, v164, v165, vcc
	v_rsq_f32_e32 v164, v164
	s_nop 0
	v_mul_f32_e32 v165, 0x45800000, v164
	v_cndmask_b32_e32 v164, v164, v165, vcc
	v_pk_fma_f32 v[144:145], v[144:145], v[164:165], v[46:47] op_sel_hi:[1,0,1]
	v_pk_fma_f32 v[142:143], v[142:143], v[164:165], v[44:45] op_sel_hi:[1,0,1]
	v_pk_fma_f32 v[138:139], v[138:139], v[164:165], v[40:41] op_sel_hi:[1,0,1]
	v_pk_fma_f32 v[140:141], v[140:141], v[164:165], v[42:43] op_sel_hi:[1,0,1]
	v_max_f32_e32 v142, 0, v142
	v_max_f32_e32 v138, 0, v138
	v_max_f32_e32 v143, 0, v143
	v_max_f32_e32 v139, 0, v139
	v_max_f32_e32 v144, 0, v144
	v_max_f32_e32 v145, 0, v145
	v_pk_mul_f32 v[142:143], v[142:143], v[142:143]
	v_pk_mul_f32 v[138:139], v[138:139], v[138:139]
	v_max_f32_e32 v140, 0, v140
	v_max_f32_e32 v141, 0, v141
	v_pk_mul_f32 v[144:145], v[144:145], v[144:145]
	v_pk_mul_f32 v[170:171], v[140:141], v[140:141]
	v_cvt_pk_bf16_f32 v140, v142, v143
	v_cvt_pk_bf16_f32 v141, v144, v145
	v_cvt_pk_bf16_f32 v142, v138, v139
	v_lshl_add_u64 v[144:145], s[20:21], 0, v[166:167]
	v_lshlrev_b64 v[138:139], 1, v[168:169]
	v_pk_fma_f32 v[130:131], v[130:131], v[164:165], v[32:33] op_sel_hi:[1,0,1]
	v_cvt_pk_bf16_f32 v143, v170, v171
	v_lshl_add_u64 v[144:145], v[144:145], 0, v[138:139]
	v_pk_fma_f32 v[136:137], v[136:137], v[164:165], v[38:39] op_sel_hi:[1,0,1]
	v_pk_fma_f32 v[134:135], v[134:135], v[164:165], v[36:37] op_sel_hi:[1,0,1]
	v_pk_fma_f32 v[132:133], v[132:133], v[164:165], v[34:35] op_sel_hi:[1,0,1]
	v_max_f32_e32 v130, 0, v130
	v_max_f32_e32 v131, 0, v131
	flat_store_dwordx4 v[144:145], v[140:143] sc1
	v_max_f32_e32 v134, 0, v134
	v_max_f32_e32 v135, 0, v135
	v_pk_mul_f32 v[140:141], v[130:131], v[130:131]
	v_max_f32_e32 v130, 0, v136
	v_max_f32_e32 v132, 0, v132
	v_max_f32_e32 v131, 0, v137
	v_max_f32_e32 v133, 0, v133
	v_pk_mul_f32 v[134:135], v[134:135], v[134:135]
	v_pk_mul_f32 v[136:137], v[130:131], v[130:131]
	v_pk_mul_f32 v[142:143], v[132:133], v[132:133]
	v_cvt_pk_bf16_f32 v130, v134, v135
	v_cvt_pk_bf16_f32 v131, v136, v137
	v_cvt_pk_bf16_f32 v132, v140, v141
	v_cvt_pk_bf16_f32 v133, v142, v143
	flat_store_dwordx4 v[144:145], v[130:133] offset:256 sc1
	s_nop 1
	v_add_u32_e32 v130, 16, v158
	v_ashrrev_i32_e32 v131, 31, v130
	v_lshlrev_b64 v[130:131], 13, v[130:131]
	v_add_f32_e32 v132, v172, v173
	v_add_f32_e32 v133, v174, v175
	v_add_f32_e32 v132, v132, v133
	v_mov_b32_e32 v133, v132
	s_nop 1
	v_permlane16_swap_b32_e32 v132, v133
	v_add_f32_e32 v132, v132, v133
	v_mov_b32_e32 v133, v132
	s_nop 1
	v_permlane32_swap_b32_e32 v132, v133
	v_add_f32_e32 v132, v132, v133
	v_fmamk_f32 v132, v132, 0x3a800000, v229
	v_cmp_gt_f32_e32 vcc, s55, v132
	v_mul_f32_e32 v133, 0x4b800000, v132
	s_nop 0
	v_cndmask_b32_e32 v132, v132, v133, vcc
	v_rsq_f32_e32 v132, v132
	s_nop 0
	v_mul_f32_e32 v133, 0x45800000, v132
	v_cndmask_b32_e32 v132, v132, v133, vcc
	v_pk_fma_f32 v[126:127], v[126:127], v[132:133], v[44:45] op_sel_hi:[1,0,1]
	v_pk_fma_f32 v[122:123], v[122:123], v[132:133], v[40:41] op_sel_hi:[1,0,1]
	v_pk_fma_f32 v[128:129], v[128:129], v[132:133], v[46:47] op_sel_hi:[1,0,1]
	v_pk_fma_f32 v[124:125], v[124:125], v[132:133], v[42:43] op_sel_hi:[1,0,1]
	v_max_f32_e32 v126, 0, v126
	v_max_f32_e32 v122, 0, v122
	v_max_f32_e32 v127, 0, v127
	v_max_f32_e32 v123, 0, v123
	v_pk_mul_f32 v[126:127], v[126:127], v[126:127]
	v_pk_mul_f32 v[134:135], v[122:123], v[122:123]
	v_max_f32_e32 v122, 0, v128
	v_max_f32_e32 v124, 0, v124
	v_max_f32_e32 v123, 0, v129
	v_max_f32_e32 v125, 0, v125
	v_pk_mul_f32 v[128:129], v[122:123], v[122:123]
	v_pk_mul_f32 v[136:137], v[124:125], v[124:125]
	v_cvt_pk_bf16_f32 v122, v126, v127
	v_lshl_add_u64 v[126:127], s[20:21], 0, v[130:131]
	v_pk_fma_f32 v[114:115], v[114:115], v[132:133], v[32:33] op_sel_hi:[1,0,1]
	v_cvt_pk_bf16_f32 v123, v128, v129
	v_cvt_pk_bf16_f32 v124, v134, v135
	v_cvt_pk_bf16_f32 v125, v136, v137
	v_lshl_add_u64 v[126:127], v[126:127], 0, v[138:139]
	v_pk_fma_f32 v[120:121], v[120:121], v[132:133], v[38:39] op_sel_hi:[1,0,1]
	v_pk_fma_f32 v[118:119], v[118:119], v[132:133], v[36:37] op_sel_hi:[1,0,1]
	v_pk_fma_f32 v[116:117], v[116:117], v[132:133], v[34:35] op_sel_hi:[1,0,1]
	v_max_f32_e32 v114, 0, v114
	v_max_f32_e32 v115, 0, v115
	flat_store_dwordx4 v[126:127], v[122:125] sc1
	v_max_f32_e32 v118, 0, v118
	v_max_f32_e32 v119, 0, v119
	v_pk_mul_f32 v[122:123], v[114:115], v[114:115]
	v_max_f32_e32 v114, 0, v120
	v_max_f32_e32 v116, 0, v116
	v_max_f32_e32 v115, 0, v121
	v_max_f32_e32 v117, 0, v117
	v_pk_mul_f32 v[118:119], v[118:119], v[118:119]
	v_pk_mul_f32 v[120:121], v[114:115], v[114:115]
	v_pk_mul_f32 v[124:125], v[116:117], v[116:117]
	v_cvt_pk_bf16_f32 v114, v118, v119
	v_cvt_pk_bf16_f32 v115, v120, v121
	v_cvt_pk_bf16_f32 v116, v122, v123
	v_cvt_pk_bf16_f32 v117, v124, v125
	flat_store_dwordx4 v[126:127], v[114:117] offset:256 sc1
	s_nop 1
	v_add_u32_e32 v114, 32, v158
	v_ashrrev_i32_e32 v115, 31, v114
	v_lshlrev_b64 v[114:115], 13, v[114:115]
	v_add_f32_e32 v116, v176, v177
	v_add_f32_e32 v117, v178, v179
	v_add_f32_e32 v116, v116, v117
	v_mov_b32_e32 v117, v116
	s_nop 1
	v_permlane16_swap_b32_e32 v116, v117
	v_add_f32_e32 v116, v116, v117
	v_mov_b32_e32 v117, v116
	s_nop 1
	v_permlane32_swap_b32_e32 v116, v117
	v_add_f32_e32 v116, v116, v117
	v_fmamk_f32 v116, v116, 0x3a800000, v229
	v_cmp_gt_f32_e32 vcc, s55, v116
	v_mul_f32_e32 v117, 0x4b800000, v116
	s_nop 0
	v_cndmask_b32_e32 v116, v116, v117, vcc
	v_rsq_f32_e32 v116, v116
	s_nop 0
	v_mul_f32_e32 v117, 0x45800000, v116
	v_cndmask_b32_e32 v116, v116, v117, vcc
	v_pk_fma_f32 v[110:111], v[110:111], v[116:117], v[44:45] op_sel_hi:[1,0,1]
	v_pk_fma_f32 v[106:107], v[106:107], v[116:117], v[40:41] op_sel_hi:[1,0,1]
	v_pk_fma_f32 v[112:113], v[112:113], v[116:117], v[46:47] op_sel_hi:[1,0,1]
	v_pk_fma_f32 v[108:109], v[108:109], v[116:117], v[42:43] op_sel_hi:[1,0,1]
	v_max_f32_e32 v110, 0, v110
	v_max_f32_e32 v106, 0, v106
	v_max_f32_e32 v111, 0, v111
	v_max_f32_e32 v107, 0, v107
	v_pk_mul_f32 v[110:111], v[110:111], v[110:111]
	v_pk_mul_f32 v[118:119], v[106:107], v[106:107]
	v_max_f32_e32 v106, 0, v112
	v_max_f32_e32 v108, 0, v108
	v_max_f32_e32 v107, 0, v113
	v_max_f32_e32 v109, 0, v109
	v_pk_mul_f32 v[112:113], v[106:107], v[106:107]
	v_pk_mul_f32 v[120:121], v[108:109], v[108:109]
	v_cvt_pk_bf16_f32 v106, v110, v111
	v_lshl_add_u64 v[110:111], s[20:21], 0, v[114:115]
	v_pk_fma_f32 v[98:99], v[98:99], v[116:117], v[32:33] op_sel_hi:[1,0,1]
	v_cvt_pk_bf16_f32 v107, v112, v113
	v_cvt_pk_bf16_f32 v108, v118, v119
	v_cvt_pk_bf16_f32 v109, v120, v121
	v_lshl_add_u64 v[110:111], v[110:111], 0, v[138:139]
	v_pk_fma_f32 v[104:105], v[104:105], v[116:117], v[38:39] op_sel_hi:[1,0,1]
	v_pk_fma_f32 v[102:103], v[102:103], v[116:117], v[36:37] op_sel_hi:[1,0,1]
	v_pk_fma_f32 v[100:101], v[100:101], v[116:117], v[34:35] op_sel_hi:[1,0,1]
	v_max_f32_e32 v98, 0, v98
	v_max_f32_e32 v99, 0, v99
	flat_store_dwordx4 v[110:111], v[106:109] sc1
	v_max_f32_e32 v102, 0, v102
	v_max_f32_e32 v103, 0, v103
	v_pk_mul_f32 v[106:107], v[98:99], v[98:99]
	v_max_f32_e32 v98, 0, v104
	v_max_f32_e32 v100, 0, v100
	v_max_f32_e32 v99, 0, v105
	v_max_f32_e32 v101, 0, v101
	v_pk_mul_f32 v[102:103], v[102:103], v[102:103]
	v_pk_mul_f32 v[104:105], v[98:99], v[98:99]
	v_pk_mul_f32 v[108:109], v[100:101], v[100:101]
	v_cvt_pk_bf16_f32 v98, v102, v103
	v_cvt_pk_bf16_f32 v99, v104, v105
	v_cvt_pk_bf16_f32 v100, v106, v107
	v_cvt_pk_bf16_f32 v101, v108, v109
	flat_store_dwordx4 v[110:111], v[98:101] offset:256 sc1
	s_nop 1
	v_add_u32_e32 v98, 48, v158
	v_ashrrev_i32_e32 v99, 31, v98
	v_lshlrev_b64 v[98:99], 13, v[98:99]
	v_add_f32_e32 v100, v184, v185
	v_add_f32_e32 v101, v186, v187
	v_add_f32_e32 v100, v100, v101
	v_mov_b32_e32 v101, v100
	s_nop 1
	v_permlane16_swap_b32_e32 v100, v101
	v_add_f32_e32 v100, v100, v101
	v_mov_b32_e32 v101, v100
	s_nop 1
	v_permlane32_swap_b32_e32 v100, v101
	v_add_f32_e32 v100, v100, v101
	v_fmamk_f32 v100, v100, 0x3a800000, v229
	v_cmp_gt_f32_e32 vcc, s55, v100
	v_mul_f32_e32 v101, 0x4b800000, v100
	s_nop 0
	v_cndmask_b32_e32 v100, v100, v101, vcc
	v_rsq_f32_e32 v100, v100
	s_nop 0
	v_mul_f32_e32 v101, 0x45800000, v100
	v_cndmask_b32_e32 v100, v100, v101, vcc
	v_pk_fma_f32 v[94:95], v[94:95], v[100:101], v[44:45] op_sel_hi:[1,0,1]
	v_pk_fma_f32 v[90:91], v[90:91], v[100:101], v[40:41] op_sel_hi:[1,0,1]
	v_pk_fma_f32 v[96:97], v[96:97], v[100:101], v[46:47] op_sel_hi:[1,0,1]
	v_pk_fma_f32 v[92:93], v[92:93], v[100:101], v[42:43] op_sel_hi:[1,0,1]
	v_max_f32_e32 v94, 0, v94
	v_max_f32_e32 v90, 0, v90
	v_max_f32_e32 v95, 0, v95
	v_max_f32_e32 v91, 0, v91
	v_pk_mul_f32 v[94:95], v[94:95], v[94:95]
	v_pk_mul_f32 v[102:103], v[90:91], v[90:91]
	v_max_f32_e32 v90, 0, v96
	v_max_f32_e32 v92, 0, v92
	v_max_f32_e32 v91, 0, v97
	v_max_f32_e32 v93, 0, v93
	v_pk_mul_f32 v[96:97], v[90:91], v[90:91]
	v_pk_mul_f32 v[104:105], v[92:93], v[92:93]
	v_cvt_pk_bf16_f32 v90, v94, v95
	v_lshl_add_u64 v[94:95], s[20:21], 0, v[98:99]
	v_pk_fma_f32 v[82:83], v[82:83], v[100:101], v[32:33] op_sel_hi:[1,0,1]
	v_cvt_pk_bf16_f32 v91, v96, v97
	v_cvt_pk_bf16_f32 v92, v102, v103
	v_cvt_pk_bf16_f32 v93, v104, v105
	v_lshl_add_u64 v[94:95], v[94:95], 0, v[138:139]
	v_pk_fma_f32 v[88:89], v[88:89], v[100:101], v[38:39] op_sel_hi:[1,0,1]
	v_pk_fma_f32 v[86:87], v[86:87], v[100:101], v[36:37] op_sel_hi:[1,0,1]
	v_pk_fma_f32 v[84:85], v[84:85], v[100:101], v[34:35] op_sel_hi:[1,0,1]
	v_max_f32_e32 v82, 0, v82
	v_max_f32_e32 v83, 0, v83
	flat_store_dwordx4 v[94:95], v[90:93] sc1
	v_max_f32_e32 v86, 0, v86
	v_max_f32_e32 v87, 0, v87
	v_pk_mul_f32 v[90:91], v[82:83], v[82:83]
	v_max_f32_e32 v82, 0, v88
	v_max_f32_e32 v84, 0, v84
	v_max_f32_e32 v83, 0, v89
	v_max_f32_e32 v85, 0, v85
	v_pk_mul_f32 v[86:87], v[86:87], v[86:87]
	v_pk_mul_f32 v[88:89], v[82:83], v[82:83]
	v_pk_mul_f32 v[92:93], v[84:85], v[84:85]
	v_cvt_pk_bf16_f32 v82, v86, v87
	v_cvt_pk_bf16_f32 v83, v88, v89
	v_cvt_pk_bf16_f32 v84, v90, v91
	v_cvt_pk_bf16_f32 v85, v92, v93
	flat_store_dwordx4 v[94:95], v[82:85] offset:256 sc1
	s_nop 1
	v_add_u32_e32 v82, 0x80, v158
	v_ashrrev_i32_e32 v83, 31, v82
	v_lshlrev_b64 v[82:83], 13, v[82:83]
	v_add_f32_e32 v84, v196, v197
	v_add_f32_e32 v85, v198, v199
	v_add_f32_e32 v84, v84, v85
	v_mov_b32_e32 v85, v84
	s_nop 1
	v_permlane16_swap_b32_e32 v84, v85
	v_add_f32_e32 v84, v84, v85
	v_mov_b32_e32 v85, v84
	s_nop 1
	v_permlane32_swap_b32_e32 v84, v85
	v_add_f32_e32 v84, v84, v85
	v_fmamk_f32 v84, v84, 0x3a800000, v229
	v_cmp_gt_f32_e32 vcc, s55, v84
	v_mul_f32_e32 v85, 0x4b800000, v84
	s_nop 0
	v_cndmask_b32_e32 v84, v84, v85, vcc
	v_rsq_f32_e32 v84, v84
	s_nop 0
	v_mul_f32_e32 v85, 0x45800000, v84
	v_cndmask_b32_e32 v84, v84, v85, vcc
	v_pk_fma_f32 v[78:79], v[78:79], v[84:85], v[44:45] op_sel_hi:[1,0,1]
	v_pk_fma_f32 v[74:75], v[74:75], v[84:85], v[40:41] op_sel_hi:[1,0,1]
	v_pk_fma_f32 v[80:81], v[80:81], v[84:85], v[46:47] op_sel_hi:[1,0,1]
	v_pk_fma_f32 v[76:77], v[76:77], v[84:85], v[42:43] op_sel_hi:[1,0,1]
	v_max_f32_e32 v78, 0, v78
	v_max_f32_e32 v74, 0, v74
	v_max_f32_e32 v79, 0, v79
	v_max_f32_e32 v75, 0, v75
	v_pk_mul_f32 v[78:79], v[78:79], v[78:79]
	v_pk_mul_f32 v[86:87], v[74:75], v[74:75]
	v_max_f32_e32 v74, 0, v80
	v_max_f32_e32 v76, 0, v76
	v_max_f32_e32 v75, 0, v81
	v_max_f32_e32 v77, 0, v77
	v_pk_mul_f32 v[80:81], v[74:75], v[74:75]
	v_pk_mul_f32 v[88:89], v[76:77], v[76:77]
	v_cvt_pk_bf16_f32 v74, v78, v79
	v_lshl_add_u64 v[78:79], s[20:21], 0, v[82:83]
	v_pk_fma_f32 v[66:67], v[66:67], v[84:85], v[32:33] op_sel_hi:[1,0,1]
	v_cvt_pk_bf16_f32 v75, v80, v81
	v_cvt_pk_bf16_f32 v76, v86, v87
	v_cvt_pk_bf16_f32 v77, v88, v89
	v_lshl_add_u64 v[78:79], v[78:79], 0, v[138:139]
	v_pk_fma_f32 v[72:73], v[72:73], v[84:85], v[38:39] op_sel_hi:[1,0,1]
	v_pk_fma_f32 v[70:71], v[70:71], v[84:85], v[36:37] op_sel_hi:[1,0,1]
	v_pk_fma_f32 v[68:69], v[68:69], v[84:85], v[34:35] op_sel_hi:[1,0,1]
	v_max_f32_e32 v66, 0, v66
	v_max_f32_e32 v67, 0, v67
	flat_store_dwordx4 v[78:79], v[74:77] sc1
	v_max_f32_e32 v70, 0, v70
	v_max_f32_e32 v71, 0, v71
	v_pk_mul_f32 v[74:75], v[66:67], v[66:67]
	v_max_f32_e32 v66, 0, v72
	v_max_f32_e32 v68, 0, v68
	v_max_f32_e32 v67, 0, v73
	v_max_f32_e32 v69, 0, v69
	v_pk_mul_f32 v[70:71], v[70:71], v[70:71]
	v_pk_mul_f32 v[72:73], v[66:67], v[66:67]
	v_pk_mul_f32 v[76:77], v[68:69], v[68:69]
	v_cvt_pk_bf16_f32 v66, v70, v71
	v_cvt_pk_bf16_f32 v67, v72, v73
	v_cvt_pk_bf16_f32 v68, v74, v75
	v_cvt_pk_bf16_f32 v69, v76, v77
	flat_store_dwordx4 v[78:79], v[66:69] offset:256 sc1
	s_nop 1
	v_add_u32_e32 v66, 0x90, v158
	v_ashrrev_i32_e32 v67, 31, v66
	v_lshlrev_b64 v[66:67], 13, v[66:67]
	v_add_f32_e32 v68, v200, v201
	v_add_f32_e32 v69, v202, v203
	v_add_f32_e32 v68, v68, v69
	v_mov_b32_e32 v69, v68
	s_nop 1
	v_permlane16_swap_b32_e32 v68, v69
	v_add_f32_e32 v68, v68, v69
	v_mov_b32_e32 v69, v68
	s_nop 1
	v_permlane32_swap_b32_e32 v68, v69
	v_add_f32_e32 v68, v68, v69
	v_fmamk_f32 v68, v68, 0x3a800000, v229
	v_cmp_gt_f32_e32 vcc, s55, v68
	v_mul_f32_e32 v69, 0x4b800000, v68
	s_nop 0
	v_cndmask_b32_e32 v68, v68, v69, vcc
	v_rsq_f32_e32 v68, v68
	s_nop 0
	v_mul_f32_e32 v69, 0x45800000, v68
	v_cndmask_b32_e32 v68, v68, v69, vcc
	v_pk_fma_f32 v[60:61], v[60:61], v[68:69], v[44:45] op_sel_hi:[1,0,1]
	v_pk_fma_f32 v[56:57], v[56:57], v[68:69], v[40:41] op_sel_hi:[1,0,1]
	v_pk_fma_f32 v[62:63], v[62:63], v[68:69], v[46:47] op_sel_hi:[1,0,1]
	v_pk_fma_f32 v[58:59], v[58:59], v[68:69], v[42:43] op_sel_hi:[1,0,1]
	v_max_f32_e32 v60, 0, v60
	v_max_f32_e32 v56, 0, v56
	v_max_f32_e32 v61, 0, v61
	v_max_f32_e32 v57, 0, v57
	v_pk_mul_f32 v[60:61], v[60:61], v[60:61]
	v_pk_mul_f32 v[70:71], v[56:57], v[56:57]
	v_max_f32_e32 v56, 0, v62
	v_max_f32_e32 v58, 0, v58
	v_max_f32_e32 v57, 0, v63
	v_max_f32_e32 v59, 0, v59
	v_pk_mul_f32 v[62:63], v[56:57], v[56:57]
	v_pk_mul_f32 v[72:73], v[58:59], v[58:59]
	v_cvt_pk_bf16_f32 v56, v60, v61
	v_lshl_add_u64 v[60:61], s[20:21], 0, v[66:67]
	v_pk_fma_f32 v[48:49], v[48:49], v[68:69], v[32:33] op_sel_hi:[1,0,1]
	v_cvt_pk_bf16_f32 v57, v62, v63
	v_cvt_pk_bf16_f32 v58, v70, v71
	v_cvt_pk_bf16_f32 v59, v72, v73
	v_lshl_add_u64 v[60:61], v[60:61], 0, v[138:139]
	v_pk_fma_f32 v[54:55], v[54:55], v[68:69], v[38:39] op_sel_hi:[1,0,1]
	v_pk_fma_f32 v[52:53], v[52:53], v[68:69], v[36:37] op_sel_hi:[1,0,1]
	v_pk_fma_f32 v[50:51], v[50:51], v[68:69], v[34:35] op_sel_hi:[1,0,1]
	v_max_f32_e32 v48, 0, v48
	v_max_f32_e32 v49, 0, v49
	flat_store_dwordx4 v[60:61], v[56:59] sc1
	v_max_f32_e32 v52, 0, v52
	v_max_f32_e32 v53, 0, v53
	v_pk_mul_f32 v[56:57], v[48:49], v[48:49]
	v_max_f32_e32 v48, 0, v54
	v_max_f32_e32 v50, 0, v50
	v_max_f32_e32 v49, 0, v55
	v_max_f32_e32 v51, 0, v51
	v_pk_mul_f32 v[52:53], v[52:53], v[52:53]
	v_pk_mul_f32 v[54:55], v[48:49], v[48:49]
	v_pk_mul_f32 v[58:59], v[50:51], v[50:51]
	v_cvt_pk_bf16_f32 v48, v52, v53
	v_cvt_pk_bf16_f32 v49, v54, v55
	v_cvt_pk_bf16_f32 v50, v56, v57
	v_cvt_pk_bf16_f32 v51, v58, v59
	flat_store_dwordx4 v[60:61], v[48:51] offset:256 sc1
	s_nop 1
	v_add_u32_e32 v48, 0xa0, v158
	v_ashrrev_i32_e32 v49, 31, v48
	v_lshlrev_b64 v[48:49], 13, v[48:49]
	v_add_f32_e32 v50, v204, v205
	v_add_f32_e32 v51, v206, v207
	v_add_f32_e32 v50, v50, v51
	v_mov_b32_e32 v51, v50
	s_nop 1
	v_permlane16_swap_b32_e32 v50, v51
	v_add_f32_e32 v50, v50, v51
	v_mov_b32_e32 v51, v50
	s_nop 1
	v_permlane32_swap_b32_e32 v50, v51
	v_add_f32_e32 v50, v50, v51
	v_fmamk_f32 v50, v50, 0x3a800000, v229
	v_cmp_gt_f32_e32 vcc, s55, v50
	v_mul_f32_e32 v51, 0x4b800000, v50
	s_nop 0
	v_cndmask_b32_e32 v50, v50, v51, vcc
	v_rsq_f32_e32 v50, v50
	s_nop 0
	v_mul_f32_e32 v51, 0x45800000, v50
	v_cndmask_b32_e32 v50, v50, v51, vcc
	v_pk_fma_f32 v[28:29], v[28:29], v[50:51], v[44:45] op_sel_hi:[1,0,1]
	v_pk_fma_f32 v[24:25], v[24:25], v[50:51], v[40:41] op_sel_hi:[1,0,1]
	v_pk_fma_f32 v[30:31], v[30:31], v[50:51], v[46:47] op_sel_hi:[1,0,1]
	v_pk_fma_f32 v[26:27], v[26:27], v[50:51], v[42:43] op_sel_hi:[1,0,1]
	v_max_f32_e32 v28, 0, v28
	v_max_f32_e32 v24, 0, v24
	v_max_f32_e32 v29, 0, v29
	v_max_f32_e32 v25, 0, v25
	v_pk_mul_f32 v[28:29], v[28:29], v[28:29]
	v_pk_mul_f32 v[52:53], v[24:25], v[24:25]
	v_max_f32_e32 v24, 0, v30
	v_max_f32_e32 v26, 0, v26
	v_max_f32_e32 v25, 0, v31
	v_max_f32_e32 v27, 0, v27
	v_pk_mul_f32 v[30:31], v[24:25], v[24:25]
	v_pk_mul_f32 v[54:55], v[26:27], v[26:27]
	v_cvt_pk_bf16_f32 v24, v28, v29
	v_lshl_add_u64 v[28:29], s[20:21], 0, v[48:49]
	v_pk_fma_f32 v[16:17], v[16:17], v[50:51], v[32:33] op_sel_hi:[1,0,1]
	v_cvt_pk_bf16_f32 v25, v30, v31
	v_cvt_pk_bf16_f32 v26, v52, v53
	v_cvt_pk_bf16_f32 v27, v54, v55
	v_lshl_add_u64 v[28:29], v[28:29], 0, v[138:139]
	v_pk_fma_f32 v[22:23], v[22:23], v[50:51], v[38:39] op_sel_hi:[1,0,1]
	v_pk_fma_f32 v[20:21], v[20:21], v[50:51], v[36:37] op_sel_hi:[1,0,1]
	v_pk_fma_f32 v[18:19], v[18:19], v[50:51], v[34:35] op_sel_hi:[1,0,1]
	v_max_f32_e32 v16, 0, v16
	v_max_f32_e32 v17, 0, v17
	flat_store_dwordx4 v[28:29], v[24:27] sc1
	v_max_f32_e32 v20, 0, v20
	v_max_f32_e32 v21, 0, v21
	v_pk_mul_f32 v[24:25], v[16:17], v[16:17]
	v_max_f32_e32 v16, 0, v22
	v_max_f32_e32 v18, 0, v18
	v_max_f32_e32 v17, 0, v23
	v_max_f32_e32 v19, 0, v19
	v_pk_mul_f32 v[20:21], v[20:21], v[20:21]
	v_pk_mul_f32 v[22:23], v[16:17], v[16:17]
	v_pk_mul_f32 v[26:27], v[18:19], v[18:19]
	v_cvt_pk_bf16_f32 v16, v20, v21
	v_cvt_pk_bf16_f32 v17, v22, v23
	v_cvt_pk_bf16_f32 v18, v24, v25
	v_cvt_pk_bf16_f32 v19, v26, v27
	flat_store_dwordx4 v[28:29], v[16:19] offset:256 sc1
	s_nop 1
	v_add_u32_e32 v16, 0xb0, v158
	v_ashrrev_i32_e32 v17, 31, v16
	v_lshlrev_b64 v[16:17], 13, v[16:17]
	v_add_f32_e32 v18, v216, v217
	v_add_f32_e32 v19, v218, v219
	v_add_f32_e32 v18, v18, v19
	v_mov_b32_e32 v19, v18
	s_nop 1
	v_permlane16_swap_b32_e32 v18, v19
	v_add_f32_e32 v18, v18, v19
	v_mov_b32_e32 v19, v18
	s_nop 1
	v_permlane32_swap_b32_e32 v18, v19
	v_add_f32_e32 v18, v18, v19
	v_fmamk_f32 v18, v18, 0x3a800000, v229
	v_cmp_gt_f32_e32 vcc, s55, v18
	v_mul_f32_e32 v19, 0x4b800000, v18
	s_nop 0
	v_cndmask_b32_e32 v18, v18, v19, vcc
	v_rsq_f32_e32 v18, v18
	s_nop 0
	v_mul_f32_e32 v19, 0x45800000, v18
	v_cndmask_b32_e32 v18, v18, v19, vcc
	v_pk_fma_f32 v[12:13], v[12:13], v[18:19], v[44:45] op_sel_hi:[1,0,1]
	v_pk_fma_f32 v[8:9], v[8:9], v[18:19], v[40:41] op_sel_hi:[1,0,1]
	v_pk_fma_f32 v[14:15], v[14:15], v[18:19], v[46:47] op_sel_hi:[1,0,1]
	v_pk_fma_f32 v[10:11], v[10:11], v[18:19], v[42:43] op_sel_hi:[1,0,1]
	v_max_f32_e32 v12, 0, v12
	v_max_f32_e32 v8, 0, v8
	v_max_f32_e32 v13, 0, v13
	v_max_f32_e32 v9, 0, v9
	v_pk_mul_f32 v[12:13], v[12:13], v[12:13]
	v_pk_mul_f32 v[20:21], v[8:9], v[8:9]
	v_max_f32_e32 v8, 0, v14
	v_max_f32_e32 v10, 0, v10
	v_max_f32_e32 v9, 0, v15
	v_max_f32_e32 v11, 0, v11
	v_pk_mul_f32 v[14:15], v[8:9], v[8:9]
	v_pk_mul_f32 v[22:23], v[10:11], v[10:11]
	v_cvt_pk_bf16_f32 v8, v12, v13
	v_lshl_add_u64 v[12:13], s[20:21], 0, v[16:17]
	v_pk_fma_f32 v[0:1], v[0:1], v[18:19], v[32:33] op_sel_hi:[1,0,1]
	v_cvt_pk_bf16_f32 v9, v14, v15
	v_cvt_pk_bf16_f32 v10, v20, v21
	v_cvt_pk_bf16_f32 v11, v22, v23
	v_lshl_add_u64 v[12:13], v[12:13], 0, v[138:139]
	v_pk_fma_f32 v[6:7], v[6:7], v[18:19], v[38:39] op_sel_hi:[1,0,1]
	v_pk_fma_f32 v[4:5], v[4:5], v[18:19], v[36:37] op_sel_hi:[1,0,1]
	v_pk_fma_f32 v[2:3], v[2:3], v[18:19], v[34:35] op_sel_hi:[1,0,1]
	v_max_f32_e32 v0, 0, v0
	v_max_f32_e32 v1, 0, v1
	flat_store_dwordx4 v[12:13], v[8:11] sc1
	v_max_f32_e32 v4, 0, v4
	v_max_f32_e32 v5, 0, v5
	v_pk_mul_f32 v[8:9], v[0:1], v[0:1]
	v_max_f32_e32 v0, 0, v6
	v_max_f32_e32 v2, 0, v2
	v_max_f32_e32 v1, 0, v7
	v_max_f32_e32 v3, 0, v3
	v_pk_mul_f32 v[4:5], v[4:5], v[4:5]
	v_pk_mul_f32 v[6:7], v[0:1], v[0:1]
	v_pk_mul_f32 v[10:11], v[2:3], v[2:3]
	v_cvt_pk_bf16_f32 v0, v4, v5
	v_cvt_pk_bf16_f32 v1, v6, v7
	v_cvt_pk_bf16_f32 v2, v8, v9
	v_cvt_pk_bf16_f32 v3, v10, v11
	s_andn2_b64 vcc, exec, s[6:7]
	flat_store_dwordx4 v[12:13], v[0:3] offset:256 sc1
	s_cbranch_vccnz .LBB0_2121
	s_andn2_b64 vcc, exec, s[18:19]
	s_cbranch_vccnz .LBB0_2120
	s_barrier
	s_branch .LBB0_2120
